# SB unit prologue waits only for Q (vmcnt 8) instead of draining all staged tiles
# baseline (speedup 1.0000x reference)
.LBB0_338:
	s_mov_b64 s[8:9], -1
	s_and_b64 vcc, exec, s[6:7]
	s_waitcnt vmcnt(8)
	s_cbranch_vccz .LBB0_340
	s_waitcnt vmcnt(8) lgkmcnt(0)
	s_barrier
	s_mov_b64 s[8:9], 0
